# seam leaders no longer issue the two release-word atomics nobody reads, so their closing wait has nothing outstanding
# baseline (speedup 1.0000x reference)
.LBB0_836:
	s_or_b64 exec, exec, s[12:13]
	v_cvt_f32_u32_e32 v4, v1
	s_waitcnt vmcnt(0)
	v_readfirstlane_b32 s0, v3
	s_add_u32 s10, s78, 0x24703500
	s_addc_u32 s11, s79, 0
	v_rcp_iflag_f32_e32 v4, v4
	v_add_u32_e32 v2, s0, v2
	s_mov_b64 s[14:15], 0
	v_mul_f32_e32 v3, 0x4f7ffffe, v4
	v_cvt_u32_f32_e32 v3, v3
	v_sub_u32_e32 v4, 0, v1
	v_mul_lo_u32 v4, v4, v3
	v_mul_hi_u32 v4, v3, v4
	v_add_u32_e32 v3, v3, v4
	v_mul_hi_u32 v3, v2, v3
	v_mul_lo_u32 v4, v3, v1
	v_sub_u32_e32 v4, v2, v4
	v_add_u32_e32 v5, 1, v3
	v_cmp_ge_u32_e32 vcc, v4, v1
	v_add_u32_e32 v2, 1, v2
	s_nop 0
	v_cndmask_b32_e32 v3, v3, v5, vcc
	v_sub_u32_e32 v5, v4, v1
	v_cndmask_b32_e32 v4, v4, v5, vcc
	v_add_u32_e32 v5, 1, v3
	v_cmp_ge_u32_e32 vcc, v4, v1
	s_nop 1
	v_cndmask_b32_e32 v4, v3, v5, vcc
	v_mul_lo_u32 v3, v1, v4
	v_add_u32_e32 v1, v3, v1
	v_cmp_ne_u32_e32 vcc, v2, v1
	v_mov_b64_e32 v[2:3], s[10:11]
	s_and_saveexec_b64 s[12:13], vcc
	s_cbranch_execz .LBB0_848
	s_add_u32 s46, s78, 0x24703400
	s_addc_u32 s47, s79, 0
	global_load_dword v5, v0, s[46:47] sc1
	s_mov_b64 s[16:17], 0
	s_waitcnt vmcnt(0)
	v_cmp_gt_u32_e32 vcc, v1, v5
	s_and_saveexec_b64 s[14:15], vcc
	s_cbranch_execz .LBB0_847
	s_mov_b32 s0, 1
	s_branch .LBB0_840

.LBB0_851:
	s_bcnt1_i32_b64 s0, s[6:7]
	v_mov_b32_e32 v1, s0
	v_mov_b32_e32 v2, 0x2000
	s_getpc_b64 s[98:99]
